# scan phase: per-step prefetch loads and LDS-DMA issue deferred into the LDS-latency waits of the o-chain (on top of GEMM early-barrier version)
# speedup vs baseline: 1.0459x; 1.0070x over previous
.LBB0_369:
	s_or_b64 exec, exec, s[54:55]
	s_lshl_b64 s[54:55], s[52:53], 8
	v_lshl_add_u64 v[4:5], s[54:55], 0, v[114:115]
	v_lshlrev_b64 v[4:5], 7, v[4:5]
	v_lshl_add_u64 v[244:245], v[138:139], 0, v[4:5]
	s_lshl_b64 s[52:53], s[52:53], 10
	v_lshl_add_u64 v[250:251], v[140:141], 0, s[52:53]
	v_add_u32_e32 v208, v180, v117
	v_add_u32_e32 v212, v180, v119
	ds_read_b128 v[100:103], v208
	ds_read_b128 v[96:99], v212
	v_add_u32_e32 v214, v181, v117
	v_add_u32_e32 v218, v181, v119
	v_add_u32_e32 v216, v180, v113
	ds_read_b128 v[104:107], v214
	ds_read_b128 v[92:95], v218
	ds_read_b128 v[224:227], v216 offset:36864
	global_load_dwordx4 v[20:23], v[244:245], off offset:0
	s_waitcnt lgkmcnt(0)
	v_cndmask_b32_e64 v223, v99, v103, s[42:43]
	v_cndmask_b32_e64 v222, v98, v102, s[42:43]
	v_cndmask_b32_e64 v221, v97, v101, s[42:43]
	v_cndmask_b32_e64 v220, v96, v100, s[42:43]
	v_add_u32_e32 v215, v181, v113
	ds_read_b128 v[228:231], v215 offset:36864
	v_mfma_f32_16x16x32_bf16 v[220:223], v[220:223], v[224:227], 0
	v_cndmask_b32_e64 v227, v95, v107, s[42:43]
	v_cndmask_b32_e64 v226, v94, v106, s[42:43]
	v_cndmask_b32_e64 v225, v93, v105, s[42:43]
	v_cndmask_b32_e64 v224, v92, v104, s[42:43]
	v_add_u32_e32 v219, v151, v154
	v_add_u32_e32 v213, v151, v155
	global_load_dwordx4 v[16:19], v[244:245], off offset:64
	s_waitcnt lgkmcnt(0)
	v_mfma_f32_16x16x32_bf16 v[220:223], v[224:227], v[228:231], v[220:223]
	ds_read_b128 v[224:227], v184
	ds_read_b128 v[228:231], v219
	v_add_u32_e32 v217, v151, v156
	s_waitcnt lgkmcnt(0)
	v_mfma_f32_16x16x32_bf16 v[220:223], v[224:227], v[228:231], v[220:223]
	ds_read_b128 v[224:227], v184 offset:64
	ds_read_b128 v[228:231], v213
	v_add_u32_e32 v209, v151, v157
	global_load_dwordx4 v[8:11], v[244:245], off offset:0x800
	s_waitcnt lgkmcnt(0)
	v_mfma_f32_16x16x32_bf16 v[220:223], v[224:227], v[228:231], v[220:223]
	ds_read_b128 v[224:227], v184 offset:128
	ds_read_b128 v[228:231], v217
	v_add_u32_e32 v210, v151, v158
	s_waitcnt lgkmcnt(0)
	v_mfma_f32_16x16x32_bf16 v[220:223], v[224:227], v[228:231], v[220:223]
	ds_read_b128 v[224:227], v184 offset:192
	ds_read_b128 v[228:231], v209
	v_add_u32_e32 v211, v151, v159
	global_load_dwordx4 v[4:7], v[244:245], off offset:0x840
	s_waitcnt lgkmcnt(0)
	v_mfma_f32_16x16x32_bf16 v[220:223], v[224:227], v[228:231], v[220:223]
	ds_read_b128 v[224:227], v184 offset:256
	ds_read_b128 v[228:231], v210
	v_pk_mul_f32 v[86:87], v[74:75], v[86:87]
	global_load_dwordx4 v[24:27], v[250:251], off offset:0
	s_waitcnt lgkmcnt(0)
	v_mfma_f32_16x16x32_bf16 v[220:223], v[224:227], v[228:231], v[220:223]
	ds_read_b128 v[224:227], v184 offset:320
	ds_read_b128 v[228:231], v211
	v_pk_mul_f32 v[84:85], v[72:73], v[84:85]
	s_waitcnt lgkmcnt(0)
	v_mfma_f32_16x16x32_bf16 v[222:225], v[224:227], v[228:231], v[220:223]
	ds_read_b128 v[226:229], v184 offset:384
	s_nop 1
	v_add_u32_e32 v220, v151, v160
	ds_read_b128 v[230:233], v220
	global_load_dwordx4 v[12:15], v[250:251], off offset:64
	s_waitcnt lgkmcnt(0)
	v_mfma_f32_16x16x32_bf16 v[222:225], v[226:229], v[230:233], v[222:225]
	ds_read_b128 v[226:229], v184 offset:448
	v_add_u32_e32 v221, v151, v161
	ds_read_b128 v[230:233], v221
	v_pk_mul_f32 v[74:75], v[74:75], v[90:91]
	v_pk_mul_f32 v[72:73], v[72:73], v[88:89]
	v_mfma_f32_16x16x32_bf16 v[84:87], v[64:67], v[100:103], v[84:87]
	s_mov_b32 s47, s9
	v_mfma_f32_16x16x32_bf16 v[64:67], v[64:67], v[96:99], v[72:75]
	s_waitcnt lgkmcnt(0)
	v_mfma_f32_16x16x32_bf16 v[222:225], v[226:229], v[230:233], v[222:225]
	v_mfma_f32_16x16x32_bf16 v[88:91], v[68:71], v[92:95], v[64:67]
	s_nop 4
	v_mul_f32_e64 v66, v62, v82
	v_mul_f32_e64 v67, v63, v83
	v_pk_mul_f32 v[64:65], v[60:61], v[80:81]
	v_pk_mul_f32 v[62:63], v[62:63], v[78:79]
	v_pk_mul_f32 v[60:61], v[60:61], v[76:77]
	v_mfma_f32_16x16x32_bf16 v[64:67], v[56:59], v[100:103], v[64:67]
	v_cvt_pk_bf16_f32 v222, v222, v223
	v_cvt_pk_bf16_f32 v223, v224, v225
	v_lshl_add_u64 v[224:225], v[144:145], 0, s[46:47]
	v_mfma_f32_16x16x32_bf16 v[56:59], v[56:59], v[96:99], v[60:63]
	v_lshlrev_b64 v[224:225], 6, v[224:225]
	v_lshl_add_u64 v[224:225], v[146:147], 0, v[224:225]
	global_store_dwordx2 v[224:225], v[222:223], off
	v_mfma_f32_16x16x32_bf16 v[84:87], v[68:71], v[104:107], v[84:87]
	s_waitcnt lgkmcnt(0)
	s_barrier
	v_mfma_f32_16x16x32_bf16 v[80:83], v[52:55], v[104:107], v[64:67]
	v_mfma_f32_16x16x32_bf16 v[76:79], v[52:55], v[92:95], v[56:59]
	s_nop 4
	v_cvt_pk_bf16_f32 v52, v84, v85
	v_cvt_pk_bf16_f32 v53, v86, v87
	ds_write_b64 v185, v[52:53]
	v_cvt_pk_bf16_f32 v52, v88, v89
	v_cvt_pk_bf16_f32 v53, v90, v91
	ds_write_b64 v185, v[52:53] offset:8448
	v_cvt_pk_bf16_f32 v52, v80, v81
	v_cvt_pk_bf16_f32 v53, v82, v83
	ds_write_b64 v186, v[52:53]
	v_cvt_pk_bf16_f32 v52, v76, v77
	v_cvt_pk_bf16_f32 v53, v78, v79
	ds_write_b64 v186, v[52:53] offset:8448
	s_waitcnt vmcnt(14) lgkmcnt(0)
	s_barrier
	s_add_i32 s87, s87, -3
	s_cmpk_gt_u32 s93, 0xf8
	s_mov_b32 s47, s93
	s_cbranch_scc1 .LBB0_376
.LBB0_370:
	s_add_i32 s8, s87, 2
	s_add_i32 s46, s47, 5
	s_and_b64 s[52:53], s[30:31], exec
	s_cselect_b32 s8, s46, s8
	s_lshl_b32 s46, s8, 6
	s_add_i32 s52, s46, s71
	s_ashr_i32 s53, s52, 31
	s_lshl_b64 s[52:53], s[52:53], 11
	s_add_u32 s52, s83, s52
	s_addc_u32 s53, s86, s53
	s_add_i32 s92, s64, 0x16000
	v_lshl_add_u64 v[234:235], v[122:123], 1, s[52:53]
	s_add_i32 s89, s64, 0x18000
	v_lshl_add_u64 v[236:237], v[124:125], 1, s[52:53]
	s_add_i32 s90, s64, 0x1a000
	v_lshl_add_u64 v[238:239], v[126:127], 1, s[52:53]
	s_add_i32 s91, s64, 0x1c000
	v_lshl_add_u64 v[240:241], v[128:129], 1, s[52:53]
	s_add_i32 s52, s8, s68
	s_ashr_i32 s53, s52, 31
	s_lshl_b64 s[54:55], s[52:53], 13
	s_add_i32 s88, s64, 0x1f000
	v_lshl_add_u64 v[242:243], v[136:137], 0, s[54:55]
	s_and_saveexec_b64 s[54:55], s[38:39]
	s_cbranch_execz .LBB0_372
	s_lshl_b64 s[94:95], s[52:53], 16
	s_add_i32 s8, s65, 0
	v_lshl_add_u64 v[52:53], v[142:143], 0, s[94:95]
	s_add_i32 m0, s8, 0x1e000
	s_nop 0
	global_load_lds_dwordx4 v[52:53], off
.LBB0_372:
	s_or_b64 exec, exec, s[54:55]
	s_lshl_b64 s[54:55], s[52:53], 8
	v_lshl_add_u64 v[52:53], s[54:55], 0, v[114:115]
	v_lshlrev_b64 v[52:53], 7, v[52:53]
	v_lshl_add_u64 v[244:245], v[138:139], 0, v[52:53]
	s_lshl_b64 s[52:53], s[52:53], 10
	v_lshl_add_u64 v[250:251], v[140:141], 0, s[52:53]
	v_add_u32_e32 v197, v148, v152
	ds_read_b128 v[92:95], v197 offset:32768
	ds_read_b128 v[96:99], v197 offset:34816
	v_add_u32_e32 v196, v149, v152
	v_add_u32_e32 v198, v148, v153
	ds_read_b128 v[104:107], v196 offset:36864
	ds_read_b128 v[200:203], v198 offset:32768
	ds_read_b128 v[208:211], v198 offset:34816
	v_add_u32_e32 v195, v149, v153
	s_mov_b32 m0, s92
	s_nop 0
	global_load_lds_dwordx4 v[234:235], off
	s_mov_b32 m0, s89
	s_nop 0
	global_load_lds_dwordx4 v[236:237], off
	s_waitcnt lgkmcnt(0)
	v_cndmask_b32_e64 v103, v99, v95, s[42:43]
	v_cndmask_b32_e64 v102, v98, v94, s[42:43]
	v_cndmask_b32_e64 v101, v97, v93, s[42:43]
	v_cndmask_b32_e64 v100, v96, v92, s[42:43]
	ds_read_b128 v[188:191], v195 offset:36864
	ds_read_b128 v[212:215], v184
	v_mfma_f32_16x16x32_bf16 v[100:103], v[100:103], v[104:107], 0
	v_cndmask_b32_e64 v107, v211, v203, s[42:43]
	v_cndmask_b32_e64 v106, v210, v202, s[42:43]
	v_cndmask_b32_e64 v105, v209, v201, s[42:43]
	v_cndmask_b32_e64 v104, v208, v200, s[42:43]
	v_add_u32_e32 v194, v150, v154
	ds_read_b128 v[216:219], v194
	s_mov_b32 m0, s90
	s_nop 0
	global_load_lds_dwordx4 v[238:239], off
	s_mov_b32 m0, s91
	s_nop 0
	global_load_lds_dwordx4 v[240:241], off
	s_waitcnt lgkmcnt(0)
	v_mfma_f32_16x16x32_bf16 v[100:103], v[104:107], v[188:191], v[100:103]
	ds_read_b128 v[104:107], v184 offset:64
	v_add_u32_e32 v193, v150, v155
	ds_read_b128 v[188:191], v193
	v_mfma_f32_16x16x32_bf16 v[100:103], v[212:215], v[216:219], v[100:103]
	ds_read_b128 v[212:215], v184 offset:128
	v_add_u32_e32 v192, v150, v156
	ds_read_b128 v[216:219], v192
	s_mov_b32 m0, s88
	s_nop 0
	global_load_lds_dwordx4 v[242:243], off
	global_load_dwordx4 v[64:67], v[244:245], off offset:0
	s_waitcnt lgkmcnt(0)
	v_mfma_f32_16x16x32_bf16 v[100:103], v[104:107], v[188:191], v[100:103]
	ds_read_b128 v[104:107], v184 offset:192
	v_add_u32_e32 v191, v150, v157
	ds_read_b128 v[220:223], v191
	v_mfma_f32_16x16x32_bf16 v[100:103], v[212:215], v[216:219], v[100:103]
	ds_read_b128 v[212:215], v184 offset:256
	v_add_u32_e32 v188, v150, v158
	ds_read_b128 v[216:219], v188
	global_load_dwordx4 v[68:71], v[244:245], off offset:64
	global_load_dwordx4 v[56:59], v[244:245], off offset:0x800
	s_waitcnt lgkmcnt(0)
	v_mfma_f32_16x16x32_bf16 v[100:103], v[104:107], v[220:223], v[100:103]
	ds_read_b128 v[104:107], v184 offset:320
	v_add_u32_e32 v187, v150, v159
	ds_read_b128 v[220:223], v187
	v_mfma_f32_16x16x32_bf16 v[100:103], v[212:215], v[216:219], v[100:103]
	ds_read_b128 v[212:215], v184 offset:384
	v_add_u32_e32 v189, v150, v160
	ds_read_b128 v[216:219], v189
	global_load_dwordx4 v[52:55], v[244:245], off offset:0x840
	global_load_dwordx4 v[72:75], v[250:251], off offset:0
	s_waitcnt lgkmcnt(0)
	v_mfma_f32_16x16x32_bf16 v[100:103], v[104:107], v[220:223], v[100:103]
	ds_read_b128 v[104:107], v184 offset:448
	v_pk_mul_f32 v[86:87], v[50:51], v[86:87]
	v_pk_mul_f32 v[84:85], v[48:49], v[84:85]
	v_pk_mul_f32 v[50:51], v[50:51], v[90:91]
	v_pk_mul_f32 v[48:49], v[48:49], v[88:89]
	v_mfma_f32_16x16x32_bf16 v[84:87], v[44:47], v[92:95], v[84:87]
	v_add_u32_e32 v190, v150, v161
	s_add_i32 s93, s47, 3
	s_add_i32 s8, s87, 4
	v_mfma_f32_16x16x32_bf16 v[44:47], v[44:47], v[96:99], v[48:51]
	s_and_b64 s[52:53], s[30:31], exec
	s_cselect_b32 s8, s93, s8
	s_lshl_b32 s8, s8, 6
	v_mfma_f32_16x16x32_bf16 v[100:103], v[212:215], v[216:219], v[100:103]
	ds_read_b128 v[212:215], v190
	v_mfma_f32_16x16x32_bf16 v[84:87], v[40:43], v[200:203], v[84:87]
	v_mfma_f32_16x16x32_bf16 v[88:91], v[40:43], v[208:211], v[44:47]
	v_mul_f32_e64 v42, v38, v82
	v_mul_f32_e64 v43, v39, v83
	v_pk_mul_f32 v[40:41], v[36:37], v[80:81]
	v_pk_mul_f32 v[38:39], v[38:39], v[78:79]
	v_pk_mul_f32 v[36:37], v[36:37], v[76:77]
	v_mfma_f32_16x16x32_bf16 v[40:43], v[32:35], v[92:95], v[40:43]
	global_load_dwordx4 v[60:63], v[250:251], off offset:64
	s_waitcnt lgkmcnt(0)
	v_mfma_f32_16x16x32_bf16 v[100:103], v[104:107], v[212:215], v[100:103]
	v_mfma_f32_16x16x32_bf16 v[32:35], v[32:35], v[96:99], v[36:39]
	v_mfma_f32_16x16x32_bf16 v[80:83], v[28:31], v[200:203], v[40:43]
	s_nop 5
	v_cvt_pk_bf16_f32 v44, v100, v101
	v_cvt_pk_bf16_f32 v45, v102, v103
	v_lshl_add_u64 v[40:41], v[144:145], 0, s[8:9]
	v_lshlrev_b64 v[36:37], 6, v[40:41]
	v_lshl_add_u64 v[36:37], v[146:147], 0, v[36:37]
	v_mfma_f32_16x16x32_bf16 v[76:79], v[28:31], v[208:211], v[32:35]
	global_store_dwordx2 v[36:37], v[44:45], off
	v_cvt_pk_bf16_f32 v28, v84, v85
	v_cvt_pk_bf16_f32 v29, v86, v87
	s_waitcnt lgkmcnt(0)
	s_barrier
	ds_write_b64 v185, v[28:29]
	v_cvt_pk_bf16_f32 v28, v88, v89
	v_cvt_pk_bf16_f32 v29, v90, v91
	ds_write_b64 v185, v[28:29] offset:8448
	v_cvt_pk_bf16_f32 v28, v80, v81
	v_cvt_pk_bf16_f32 v29, v82, v83
	ds_write_b64 v186, v[28:29]
	v_cvt_pk_bf16_f32 v28, v76, v77
	v_cvt_pk_bf16_f32 v29, v78, v79
	ds_write_b64 v186, v[28:29] offset:8448
	s_waitcnt vmcnt(14) lgkmcnt(0)
	s_barrier
	s_add_i32 s8, s87, 1
	s_add_i32 s54, s47, 6
	s_and_b64 s[52:53], s[30:31], exec
	s_cselect_b32 s8, s54, s8
	s_lshl_b32 s52, s8, 6
	s_add_i32 s52, s52, s71
	s_ashr_i32 s53, s52, 31
	s_lshl_b64 s[52:53], s[52:53], 11
	s_add_u32 s52, s83, s52
	s_addc_u32 s53, s86, s53
	v_lshl_add_u64 v[234:235], v[122:123], 1, s[52:53]
	v_lshl_add_u64 v[236:237], v[124:125], 1, s[52:53]
	v_lshl_add_u64 v[238:239], v[126:127], 1, s[52:53]
	v_lshl_add_u64 v[240:241], v[128:129], 1, s[52:53]
	s_add_i32 s52, s8, s68
	s_ashr_i32 s53, s52, 31
	s_lshl_b64 s[54:55], s[52:53], 13
	v_lshl_add_u64 v[242:243], v[136:137], 0, s[54:55]
	s_and_saveexec_b64 s[54:55], s[38:39]
	s_cbranch_execz .LBB0_374
	s_lshl_b64 s[94:95], s[52:53], 16
	v_lshl_add_u64 v[28:29], v[142:143], 0, s[94:95]
	s_add_i32 m0, s66, 0x8000
	s_nop 0
	global_load_lds_dwordx4 v[28:29], off
.LBB0_374:
	s_or_b64 exec, exec, s[54:55]
	s_lshl_b64 s[54:55], s[52:53], 8
	v_lshl_add_u64 v[28:29], s[54:55], 0, v[114:115]
	v_lshlrev_b64 v[28:29], 7, v[28:29]
	v_lshl_add_u64 v[244:245], v[138:139], 0, v[28:29]
	s_lshl_b64 s[52:53], s[52:53], 10
	v_lshl_add_u64 v[250:251], v[140:141], 0, s[52:53]
	v_add_u32_e32 v199, v162, v117
	v_add_u32_e32 v200, v162, v119
	ds_read_b128 v[104:107], v199
	ds_read_b128 v[96:99], v200
	v_add_u32_e32 v201, v163, v117
	v_add_u32_e32 v202, v163, v119
	v_add_u32_e32 v203, v162, v113
	ds_read_b128 v[100:103], v201
	ds_read_b128 v[92:95], v202
	s_mov_b32 m0, s64
	s_nop 0
	global_load_lds_dwordx4 v[234:235], off
	s_mov_b32 m0, s73
	s_nop 0
	global_load_lds_dwordx4 v[236:237], off
	s_waitcnt lgkmcnt(0)
	v_cndmask_b32_e64 v211, v99, v107, s[42:43]
	v_cndmask_b32_e64 v210, v98, v106, s[42:43]
	v_cndmask_b32_e64 v209, v97, v105, s[42:43]
	v_cndmask_b32_e64 v208, v96, v104, s[42:43]
	ds_read_b128 v[212:215], v203 offset:36864
	v_add_u32_e32 v207, v163, v113
	ds_read_b128 v[216:219], v207 offset:36864
	s_mov_b32 m0, s74
	s_nop 0
	global_load_lds_dwordx4 v[238:239], off
	s_waitcnt lgkmcnt(0)
	v_mfma_f32_16x16x32_bf16 v[208:211], v[208:211], v[212:215], 0
	v_cndmask_b32_e64 v215, v95, v103, s[42:43]
	v_cndmask_b32_e64 v214, v94, v102, s[42:43]
	v_cndmask_b32_e64 v213, v93, v101, s[42:43]
	v_cndmask_b32_e64 v212, v92, v100, s[42:43]
	v_pk_mul_f32 v[86:87], v[26:27], v[86:87]
	v_pk_mul_f32 v[84:85], v[24:25], v[84:85]
	v_mfma_f32_16x16x32_bf16 v[208:211], v[212:215], v[216:219], v[208:211]
	ds_read_b128 v[212:215], v184
	ds_read_b128 v[216:219], v194 offset:45056
	v_pk_mul_f32 v[26:27], v[26:27], v[90:91]
	v_pk_mul_f32 v[24:25], v[24:25], v[88:89]
	s_mov_b32 m0, s75
	s_nop 0
	global_load_lds_dwordx4 v[240:241], off
	s_waitcnt lgkmcnt(0)
	v_mfma_f32_16x16x32_bf16 v[208:211], v[212:215], v[216:219], v[208:211]
	ds_read_b128 v[212:215], v184 offset:64
	ds_read_b128 v[216:219], v193 offset:45056
	s_add_i32 s8, s47, 4
	s_add_i32 s54, s87, 3
	s_mov_b32 m0, s78
	s_nop 0
	global_load_lds_dwordx4 v[242:243], off
	s_waitcnt lgkmcnt(0)
	v_mfma_f32_16x16x32_bf16 v[208:211], v[212:215], v[216:219], v[208:211]
	ds_read_b128 v[212:215], v184 offset:128
	ds_read_b128 v[216:219], v192 offset:45056
	s_and_b64 s[52:53], s[30:31], exec
	s_cselect_b32 s8, s8, s54
	global_load_dwordx4 v[44:47], v[244:245], off offset:0
	s_waitcnt lgkmcnt(0)
	v_mfma_f32_16x16x32_bf16 v[208:211], v[212:215], v[216:219], v[208:211]
	ds_read_b128 v[212:215], v184 offset:192
	ds_read_b128 v[216:219], v191 offset:45056
	s_lshl_b32 s8, s8, 6
	global_load_dwordx4 v[40:43], v[244:245], off offset:64
	s_waitcnt lgkmcnt(0)
	v_mfma_f32_16x16x32_bf16 v[208:211], v[212:215], v[216:219], v[208:211]
	ds_read_b128 v[212:215], v184 offset:256
	ds_read_b128 v[216:219], v188 offset:45056
	global_load_dwordx4 v[32:35], v[244:245], off offset:0x800
	s_waitcnt lgkmcnt(0)
	v_mfma_f32_16x16x32_bf16 v[208:211], v[212:215], v[216:219], v[208:211]
	ds_read_b128 v[212:215], v184 offset:320
	ds_read_b128 v[216:219], v187 offset:45056
	global_load_dwordx4 v[28:31], v[244:245], off offset:0x840
	s_waitcnt lgkmcnt(0)
	v_mfma_f32_16x16x32_bf16 v[208:211], v[212:215], v[216:219], v[208:211]
	ds_read_b128 v[212:215], v184 offset:384
	ds_read_b128 v[216:219], v189 offset:45056
	global_load_dwordx4 v[48:51], v[250:251], off offset:0
	s_waitcnt lgkmcnt(0)
	v_mfma_f32_16x16x32_bf16 v[208:211], v[212:215], v[216:219], v[208:211]
	ds_read_b128 v[212:215], v184 offset:448
	ds_read_b128 v[216:219], v190 offset:45056
	v_mfma_f32_16x16x32_bf16 v[84:87], v[20:23], v[104:107], v[84:87]
	v_mfma_f32_16x16x32_bf16 v[20:23], v[20:23], v[96:99], v[24:27]
	global_load_dwordx4 v[36:39], v[250:251], off offset:64
	s_waitcnt lgkmcnt(0)
	v_mfma_f32_16x16x32_bf16 v[208:211], v[212:215], v[216:219], v[208:211]
	v_mfma_f32_16x16x32_bf16 v[84:87], v[16:19], v[100:103], v[84:87]
	v_mfma_f32_16x16x32_bf16 v[88:91], v[16:19], v[92:95], v[20:23]
	v_mul_f32_e64 v18, v14, v82
	v_mul_f32_e64 v19, v15, v83
	v_pk_mul_f32 v[16:17], v[12:13], v[80:81]
	v_pk_mul_f32 v[14:15], v[14:15], v[78:79]
	v_pk_mul_f32 v[12:13], v[12:13], v[76:77]
	v_mfma_f32_16x16x32_bf16 v[16:19], v[8:11], v[104:107], v[16:19]
	v_cvt_pk_bf16_f32 v208, v208, v209
	v_cvt_pk_bf16_f32 v209, v210, v211
	v_lshl_add_u64 v[210:211], v[144:145], 0, s[8:9]
	v_mfma_f32_16x16x32_bf16 v[8:11], v[8:11], v[96:99], v[12:15]
	v_lshlrev_b64 v[210:211], 6, v[210:211]
	v_lshl_add_u64 v[210:211], v[146:147], 0, v[210:211]
	global_store_dwordx2 v[210:211], v[208:209], off
	v_mfma_f32_16x16x32_bf16 v[80:83], v[4:7], v[100:103], v[16:19]
	s_waitcnt lgkmcnt(0)
	s_barrier
	v_mfma_f32_16x16x32_bf16 v[76:79], v[4:7], v[92:95], v[8:11]
	v_cvt_pk_bf16_f32 v4, v84, v85
	v_cvt_pk_bf16_f32 v5, v86, v87
	ds_write_b64 v185, v[4:5]
	v_cvt_pk_bf16_f32 v4, v88, v89
	v_cvt_pk_bf16_f32 v5, v90, v91
	ds_write_b64 v185, v[4:5] offset:8448
	v_cvt_pk_bf16_f32 v4, v80, v81
	v_cvt_pk_bf16_f32 v5, v82, v83
	ds_write_b64 v186, v[4:5]
	v_cvt_pk_bf16_f32 v4, v76, v77
	v_cvt_pk_bf16_f32 v5, v78, v79
	ds_write_b64 v186, v[4:5] offset:8448
	s_waitcnt vmcnt(14) lgkmcnt(0)
	s_barrier
	s_add_i32 s8, s47, 7
	s_and_b64 s[52:53], s[30:31], exec
	s_cselect_b32 s8, s8, s87
	s_lshl_b32 s47, s8, 6
	s_add_i32 s52, s47, s71
	s_ashr_i32 s53, s52, 31
	s_lshl_b64 s[52:53], s[52:53], 11
	s_add_u32 s52, s83, s52
	s_addc_u32 s53, s86, s53
	s_mov_b32 m0, s67
	v_lshl_add_u64 v[4:5], v[122:123], 1, s[52:53]
	global_load_lds_dwordx4 v[4:5], off
	v_lshl_add_u64 v[4:5], v[124:125], 1, s[52:53]
	s_mov_b32 m0, s79
	s_nop 0
	global_load_lds_dwordx4 v[4:5], off
	v_lshl_add_u64 v[4:5], v[126:127], 1, s[52:53]
	s_mov_b32 m0, s80
	s_nop 0
	global_load_lds_dwordx4 v[4:5], off
	v_lshl_add_u64 v[4:5], v[128:129], 1, s[52:53]
	s_add_i32 s52, s8, s68
	s_ashr_i32 s53, s52, 31
	s_mov_b32 m0, s81
	s_lshl_b64 s[54:55], s[52:53], 13
	global_load_lds_dwordx4 v[4:5], off
	v_lshl_add_u64 v[4:5], v[136:137], 0, s[54:55]
	s_mov_b32 m0, s82
	s_nop 0
	global_load_lds_dwordx4 v[4:5], off
	s_and_saveexec_b64 s[54:55], s[38:39]
	s_cbranch_execz .LBB0_369
	s_lshl_b64 s[94:95], s[52:53], 16
	s_add_i32 s8, s65, 0
	v_lshl_add_u64 v[4:5], v[142:143], 0, s[94:95]
	s_add_i32 m0, s8, 0x13000
	s_nop 0
	global_load_lds_dwordx4 v[4:5], off
	s_branch .LBB0_369
